# v76: mode-0 attention reads-first in both unrolled steps (second step's first K-fragment ds_reads issued right after the barrier, before the conditional DMA and the 16 exps; DMA temp moved to v[238:23
# baseline (speedup 1.0000x reference)
.LBB0_385:
	s_waitcnt vmcnt(0)
	s_cmp_ge_i32 s29, s54
	s_barrier
	s_setprio 3
	v_add_u32_e32 v94, s3, v159
	ds_read_b128 v[2:5], v94
	ds_read_b128 v[6:9], v94 offset:512
	s_cbranch_scc1 .LBB0_387
	s_add_i32 s56, s56, -2
	s_ashr_i32 s58, s56, 2
	s_ashr_i32 s59, s58, 31
	s_and_b32 s56, s56, 3
	s_lshl_b64 s[58:59], s[58:59], 21
	v_lshl_add_u64 v[238:239], v[152:153], 0, s[58:59]
	s_mul_i32 s78, s56, 0x38000
	s_add_i32 s56, s57, s27
	v_lshl_add_u64 v[238:239], v[238:239], 0, s[78:79]
	s_mov_b32 m0, s56
	s_nop 0
	global_load_lds_dwordx4 v[238:239], off
	v_lshl_add_u64 v[238:239], v[156:157], 0, s[58:59]
	v_lshl_add_u64 v[238:239], v[238:239], 0, s[78:79]
	s_add_i32 m0, s56, 0x2000
	s_nop 0
	global_load_lds_dwordx4 v[238:239], off
.LBB0_387:
	v_exp_f32_e32 v122, v81
	v_exp_f32_e32 v123, v80
	v_exp_f32_e32 v124, v67
	v_exp_f32_e32 v125, v66
	v_exp_f32_e32 v126, v69
	v_exp_f32_e32 v127, v68
	v_exp_f32_e32 v128, v71
	v_exp_f32_e32 v129, v70
	v_exp_f32_e32 v130, v73
	v_exp_f32_e32 v131, v72
	v_exp_f32_e32 v132, v75
	v_exp_f32_e32 v133, v74
	v_exp_f32_e32 v134, v77
	v_exp_f32_e32 v135, v76
	v_exp_f32_e32 v136, v79
	v_exp_f32_e32 v137, v78
	v_exp_f32_e32 v138, v87
	v_exp_f32_e32 v139, v86
	v_exp_f32_e32 v140, v89
	s_waitcnt lgkmcnt(0)
	v_mfma_f32_32x32x16_bf16 v[66:81], v[2:5], v[110:113], v[16:31]
	ds_read_b128 v[2:5], v94 offset:2048
	ds_read_b128 v[10:13], v94 offset:2560
	v_exp_f32_e32 v141, v88
	v_exp_f32_e32 v142, v91
	v_exp_f32_e32 v143, v90
	v_exp_f32_e32 v144, v93
	v_exp_f32_e32 v165, v92
	s_waitcnt lgkmcnt(0)
	v_mfma_f32_32x32x16_bf16 v[66:81], v[2:5], v[106:109], v[66:81]
	ds_read_b128 v[2:5], v94 offset:4096
	ds_read_b128 v[114:117], v94 offset:4608
	s_waitcnt lgkmcnt(0)
	v_mfma_f32_32x32x16_bf16 v[66:81], v[2:5], v[102:105], v[66:81]
	ds_read_b128 v[2:5], v94 offset:6144
	ds_read_b128 v[118:121], v94 offset:6656
	s_waitcnt lgkmcnt(0)
	v_mfma_f32_32x32x16_bf16 v[66:81], v[2:5], v[98:101], v[66:81]
	v_exp_f32_e32 v2, v15
	v_exp_f32_e32 v3, v14
	v_exp_f32_e32 v4, v65
	v_exp_f32_e32 v5, v64
	v_exp_f32_e32 v14, v83
	v_exp_f32_e32 v15, v82
	v_exp_f32_e32 v64, v85
	v_exp_f32_e32 v65, v84
	v_mfma_f32_32x32x16_bf16 v[82:97], v[6:9], v[110:113], v[16:31]
	v_add_f32_e32 v6, v122, v123
	v_add_f32_e32 v6, v124, v6
	v_add_f32_e32 v6, v125, v6
	v_add_f32_e32 v6, v126, v6
	v_add_f32_e32 v6, v127, v6
	v_add_f32_e32 v6, v128, v6
	v_add_f32_e32 v6, v129, v6
	v_mfma_f32_32x32x16_bf16 v[82:97], v[10:13], v[106:109], v[82:97]
	v_add_f32_e32 v6, v130, v6
	v_add_f32_e32 v6, v131, v6
	v_add_f32_e32 v6, v132, v6
	v_add_f32_e32 v6, v133, v6
	v_add_f32_e32 v6, v134, v6
	v_add_f32_e32 v6, v135, v6
	v_add_f32_e32 v6, v136, v6
	v_mfma_f32_32x32x16_bf16 v[82:97], v[114:117], v[102:105], v[82:97]
	v_add_f32_e32 v6, v137, v6
	v_add_f32_e32 v6, v2, v6
	v_add_f32_e32 v6, v3, v6
	v_add_f32_e32 v6, v4, v6
	v_add_f32_e32 v6, v5, v6
	v_add_f32_e32 v6, v14, v6
	v_add_f32_e32 v6, v15, v6
	v_add_f32_e32 v6, v64, v6
	v_add_f32_e32 v6, v65, v6
	v_mfma_f32_32x32x16_bf16 v[82:97], v[118:121], v[98:101], v[82:97]
	v_add_f32_e32 v6, v138, v6
	v_add_f32_e32 v6, v139, v6
	v_add_f32_e32 v6, v140, v6
	v_add_f32_e32 v6, v141, v6
	v_add_f32_e32 v6, v142, v6
	v_add_f32_e32 v6, v143, v6
	v_add_f32_e32 v168, v144, v6
	v_cvt_pk_bf16_f32 v6, v2, v3
	s_setprio 2
	v_cvt_pk_bf16_f32 v2, v138, v139
	v_cvt_pk_bf16_f32 v122, v122, v123
	v_cvt_pk_bf16_f32 v123, v124, v125
	v_cvt_pk_bf16_f32 v124, v126, v127
	v_cvt_pk_bf16_f32 v125, v128, v129
	v_cvt_pk_bf16_f32 v114, v130, v131
	v_cvt_pk_bf16_f32 v115, v132, v133
	v_cvt_pk_bf16_f32 v116, v134, v135
	v_cvt_pk_bf16_f32 v117, v136, v137
	v_cvt_pk_bf16_f32 v7, v4, v5
	v_cvt_pk_bf16_f32 v8, v14, v15
	v_cvt_pk_bf16_f32 v9, v64, v65
	v_cvt_pk_bf16_f32 v3, v140, v141
	v_cvt_pk_bf16_f32 v4, v142, v143
	v_cvt_pk_bf16_f32 v5, v144, v165
	v_cvt_f32_i32_e32 v14, v162
	v_add_u32_e32 v12, s2, v0
	ds_read_b64_tr_b16 v[146:147], v12 offset:8192
	ds_read_b64_tr_b16 v[148:149], v12 offset:8704
	ds_read_b64_tr_b16 v[130:131], v12 offset:12288
	ds_read_b64_tr_b16 v[132:133], v12 offset:12800
	ds_read_b64_tr_b16 v[138:139], v12 offset:9216
	ds_read_b64_tr_b16 v[140:141], v12 offset:9728
	ds_read_b64_tr_b16 v[126:127], v12 offset:13312
	ds_read_b64_tr_b16 v[128:129], v12 offset:13824
	ds_read_b64_tr_b16 v[134:135], v12 offset:10240
	ds_read_b64_tr_b16 v[136:137], v12 offset:10752
	ds_read_b64_tr_b16 v[118:119], v12 offset:14336
	ds_read_b64_tr_b16 v[120:121], v12 offset:14848
	ds_read_b64_tr_b16 v[142:143], v12 offset:11264
	ds_read_b64_tr_b16 v[144:145], v12 offset:11776
	ds_read_b64_tr_b16 v[10:11], v12 offset:15360
	ds_read_b64_tr_b16 v[12:13], v12 offset:15872
	s_waitcnt lgkmcnt(14)
	v_mfma_f32_32x32x16_bf16 v[32:47], v[146:149], v[122:125], v[32:47]
	v_add_f32_e32 v15, 1.0, v14
	v_and_b32_e32 v64, 0x7fffffff, v14
	v_and_b32_e32 v65, 0x7fffffff, v15
	v_fma_f32 v64, v154, v64, v66
	v_fma_f32 v65, v155, v65, v67
	v_cmp_le_f32_e64 vcc, |v14|, s77
	v_cmp_le_f32_e64 s[2:3], |v15|, s77
	s_mov_b32 s78, s76
	v_cndmask_b32_e32 v164, v197, v64, vcc
	v_cndmask_b32_e64 v163, v197, v65, s[2:3]
	v_pk_add_f32 v[64:65], v[14:15], s[26:27] op_sel_hi:[1,0]
	s_waitcnt lgkmcnt(12)
	v_mfma_f32_32x32x16_bf16 v[48:63], v[130:133], v[122:125], v[48:63]
	v_and_b32_e32 v67, 0x7fffffff, v65
	v_and_b32_e32 v66, 0x7fffffff, v64
	v_fma_f32 v66, v154, v66, v82
	v_fma_f32 v67, v155, v67, v83
	v_cmp_le_f32_e64 vcc, |v64|, s77
	v_cmp_le_f32_e64 s[2:3], |v65|, s77
	v_pk_add_f32 v[82:83], v[14:15], s[8:9] op_sel_hi:[0,1]
	v_cndmask_b32_e32 v64, v197, v66, vcc
	v_cndmask_b32_e64 v65, v197, v67, s[2:3]
	v_pk_add_f32 v[66:67], v[82:83], s[26:27] op_sel_hi:[1,0]
	s_waitcnt lgkmcnt(10)
	v_mfma_f32_32x32x16_bf16 v[32:47], v[138:141], v[114:117], v[32:47]
	v_and_b32_e32 v167, 0x7fffffff, v67
	v_and_b32_e32 v166, 0x7fffffff, v66
	v_fma_f32 v84, v154, v166, v84
	v_fma_f32 v85, v155, v167, v85
	v_cmp_le_f32_e64 vcc, |v66|, s77
	v_cmp_le_f32_e64 s[2:3], |v67|, s77
	s_nop 0
	v_cndmask_b32_e32 v66, v197, v84, vcc
	v_cndmask_b32_e64 v67, v197, v85, s[2:3]
	v_and_b32_e32 v85, 0x7fffffff, v83
	v_and_b32_e32 v84, 0x7fffffff, v82
	v_pk_fma_f32 v[68:69], v[154:155], v[84:85], v[68:69]
	v_cmp_le_f32_e64 s[2:3], |v83|, s77
	v_cmp_le_f32_e64 vcc, |v82|, s77
	s_waitcnt lgkmcnt(8)
	v_mfma_f32_32x32x16_bf16 v[48:63], v[126:129], v[114:117], v[48:63]
	v_cndmask_b32_e64 v15, v197, v69, s[2:3]
	v_add_f32_e64 v84, v14, s10
	v_add_f32_e64 v85, v14, s11
	v_cndmask_b32_e32 v82, v197, v68, vcc
	v_add_f32_e64 v68, v84, s26
	v_add_f32_e64 v69, v85, s26
	v_and_b32_e32 v167, 0x7fffffff, v69
	v_and_b32_e32 v166, 0x7fffffff, v68
	v_pk_fma_f32 v[86:87], v[154:155], v[166:167], v[86:87]
	v_cmp_le_f32_e64 vcc, |v68|, s77
	v_cmp_le_f32_e64 s[2:3], |v69|, s77
	s_waitcnt lgkmcnt(6)
	v_mfma_f32_32x32x16_bf16 v[32:47], v[134:137], v[6:9], v[32:47]
	v_cndmask_b32_e32 v68, v197, v86, vcc
	v_cndmask_b32_e64 v69, v197, v87, s[2:3]
	v_and_b32_e32 v87, 0x7fffffff, v85
	v_and_b32_e32 v86, 0x7fffffff, v84
	v_fma_f32 v70, v154, v86, v70
	v_fma_f32 v71, v155, v87, v71
	v_cmp_le_f32_e64 vcc, |v84|, s77
	v_cmp_le_f32_e64 s[2:3], |v85|, s77
	v_pk_add_f32 v[86:87], v[14:15], s[12:13] op_sel_hi:[0,1]
	v_cndmask_b32_e32 v84, v197, v70, vcc
	v_cndmask_b32_e64 v83, v197, v71, s[2:3]
	v_pk_add_f32 v[70:71], v[86:87], s[26:27] op_sel_hi:[1,0]
	s_waitcnt lgkmcnt(4)
	v_mfma_f32_32x32x16_bf16 v[48:63], v[118:121], v[6:9], v[48:63]
	v_and_b32_e32 v167, 0x7fffffff, v71
	s_setprio 1
	v_and_b32_e32 v166, 0x7fffffff, v70
	v_fma_f32 v88, v154, v166, v88
	v_fma_f32 v89, v155, v167, v89
	v_cmp_le_f32_e64 vcc, |v70|, s77
	v_cmp_le_f32_e64 s[2:3], |v71|, s77
	s_nop 0
	v_cndmask_b32_e32 v70, v197, v88, vcc
	v_cndmask_b32_e64 v71, v197, v89, s[2:3]
	v_and_b32_e32 v89, 0x7fffffff, v87
	v_and_b32_e32 v88, 0x7fffffff, v86
	v_pk_fma_f32 v[72:73], v[154:155], v[88:89], v[72:73]
	v_cmp_le_f32_e64 vcc, |v86|, s77
	v_cmp_le_f32_e64 s[2:3], |v87|, s77
	v_pk_add_f32 v[88:89], v[14:15], s[14:15] op_sel_hi:[0,1]
	v_cndmask_b32_e32 v86, v197, v72, vcc
	v_cndmask_b32_e64 v85, v197, v73, s[2:3]
	v_pk_add_f32 v[72:73], v[88:89], s[26:27] op_sel_hi:[1,0]
	s_waitcnt lgkmcnt(2)
	v_mfma_f32_32x32x16_bf16 v[32:47], v[142:145], v[2:5], v[32:47]
	v_and_b32_e32 v167, 0x7fffffff, v73
	v_and_b32_e32 v166, 0x7fffffff, v72
	v_fma_f32 v90, v154, v166, v90
	v_fma_f32 v91, v155, v167, v91
	v_cmp_le_f32_e64 vcc, |v72|, s77
	v_cmp_le_f32_e64 s[2:3], |v73|, s77
	s_nop 0
	v_cndmask_b32_e32 v72, v197, v90, vcc
	v_cndmask_b32_e64 v73, v197, v91, s[2:3]
	v_and_b32_e32 v91, 0x7fffffff, v89
	v_and_b32_e32 v90, 0x7fffffff, v88
	v_pk_fma_f32 v[74:75], v[154:155], v[90:91], v[74:75]
	v_cmp_le_f32_e64 vcc, |v88|, s77
	v_cmp_le_f32_e64 s[2:3], |v89|, s77
	v_pk_add_f32 v[90:91], v[14:15], s[16:17] op_sel_hi:[0,1]
	v_cndmask_b32_e32 v88, v197, v74, vcc
	v_cndmask_b32_e64 v87, v197, v75, s[2:3]
	v_pk_add_f32 v[74:75], v[90:91], s[26:27] op_sel_hi:[1,0]
	s_waitcnt lgkmcnt(0)
	v_mfma_f32_32x32x16_bf16 v[48:63], v[10:13], v[2:5], v[48:63]
	v_and_b32_e32 v167, 0x7fffffff, v75
	v_and_b32_e32 v166, 0x7fffffff, v74
	v_fma_f32 v92, v154, v166, v92
	v_fma_f32 v93, v155, v167, v93
	v_cmp_le_f32_e64 vcc, |v74|, s77
	v_cmp_le_f32_e64 s[2:3], |v75|, s77
	s_nop 0
	v_cndmask_b32_e32 v74, v197, v92, vcc
	v_cndmask_b32_e64 v75, v197, v93, s[2:3]
	v_and_b32_e32 v93, 0x7fffffff, v91
	v_and_b32_e32 v92, 0x7fffffff, v90
	v_pk_fma_f32 v[76:77], v[154:155], v[92:93], v[76:77]
	v_cmp_le_f32_e64 vcc, |v90|, s77
	v_cmp_le_f32_e64 s[2:3], |v91|, s77
	v_pk_add_f32 v[92:93], v[14:15], s[18:19] op_sel_hi:[0,1]
	v_cndmask_b32_e32 v90, v197, v76, vcc
	v_cndmask_b32_e64 v89, v197, v77, s[2:3]
	v_pk_add_f32 v[76:77], v[92:93], s[26:27] op_sel_hi:[1,0]
	s_nop 0
	v_and_b32_e32 v167, 0x7fffffff, v77
	v_and_b32_e32 v166, 0x7fffffff, v76
	v_pk_fma_f32 v[94:95], v[154:155], v[166:167], v[94:95]
	v_cmp_le_f32_e64 vcc, |v76|, s77
	v_cmp_le_f32_e64 s[2:3], |v77|, s77
	s_nop 0
	v_cndmask_b32_e32 v76, v197, v94, vcc
	v_cndmask_b32_e64 v77, v197, v95, s[2:3]
	v_and_b32_e32 v95, 0x7fffffff, v93
	v_and_b32_e32 v94, 0x7fffffff, v92
	v_pk_fma_f32 v[78:79], v[154:155], v[94:95], v[78:79]
	v_cmp_le_f32_e64 vcc, |v92|, s77
	v_cmp_le_f32_e64 s[2:3], |v93|, s77
	v_pk_add_f32 v[94:95], v[14:15], s[20:21] op_sel_hi:[0,1]
	v_cndmask_b32_e32 v92, v197, v78, vcc
	v_cndmask_b32_e64 v91, v197, v79, s[2:3]
	v_pk_add_f32 v[78:79], v[94:95], s[26:27] op_sel_hi:[1,0]
	v_max_f32_e32 v93, v163, v65
	v_and_b32_e32 v167, 0x7fffffff, v79
	v_and_b32_e32 v166, 0x7fffffff, v78
	v_pk_fma_f32 v[96:97], v[154:155], v[166:167], v[96:97]
	v_cmp_le_f32_e64 vcc, |v78|, s77
	v_max3_f32 v93, v93, v15, v67
	v_max3_f32 v93, v93, v83, v69
	v_cndmask_b32_e32 v78, v197, v96, vcc
	v_and_b32_e32 v96, 0x7fffffff, v94
	v_cmp_le_f32_e64 vcc, |v94|, s77
	v_max3_f32 v94, v164, v64, v82
	v_max3_f32 v94, v94, v66, v84
	v_cmp_le_f32_e64 s[2:3], |v79|, s77
	v_max3_f32 v94, v94, v68, v86
	v_max3_f32 v93, v93, v85, v71
	v_cndmask_b32_e64 v79, v197, v97, s[2:3]
	v_and_b32_e32 v97, 0x7fffffff, v95
	v_max3_f32 v94, v94, v70, v88
	v_max3_f32 v93, v93, v87, v73
	v_pk_fma_f32 v[80:81], v[154:155], v[96:97], v[80:81]
	v_cmp_le_f32_e64 s[2:3], |v95|, s77
	v_max3_f32 v94, v94, v72, v90
	v_max3_f32 v93, v93, v89, v75
	v_cndmask_b32_e64 v14, v197, v81, s[2:3]
	v_cndmask_b32_e32 v80, v197, v80, vcc
	v_max3_f32 v94, v94, v74, v92
	v_max3_f32 v93, v93, v91, v77
	v_max3_f32 v94, v94, v76, v80
	v_max3_f32 v93, v93, v14, v79
	v_add_f32_e32 v81, v165, v168
	s_setprio 0
	v_max3_f32 v2, v94, v78, v93
	v_add_f32_e32 v161, v161, v81
	v_cmp_lt_f32_e32 vcc, s33, v2
	s_cbranch_vccz .LBB0_389
	v_mov_b32_e32 v3, v2
	s_nop 1
	v_permlane32_swap_b32 v2, v3
	s_nop 1
	s_nop 0
	v_max3_f32 v3, v2, v3, 0
	v_exp_f32_e64 v2, -v3
	v_add_f32_e32 v151, v151, v3
	v_xor_b32_e32 v16, 0x80000000, v151
	v_sub_f32_e32 v164, v164, v3
	v_pk_mul_f32 v[46:47], v[46:47], v[2:3] op_sel_hi:[1,0]
	v_pk_mul_f32 v[44:45], v[44:45], v[2:3] op_sel_hi:[1,0]
	v_pk_mul_f32 v[42:43], v[42:43], v[2:3] op_sel_hi:[1,0]
	v_pk_mul_f32 v[40:41], v[40:41], v[2:3] op_sel_hi:[1,0]
	v_pk_mul_f32 v[38:39], v[38:39], v[2:3] op_sel_hi:[1,0]
	v_pk_mul_f32 v[36:37], v[36:37], v[2:3] op_sel_hi:[1,0]
	v_pk_mul_f32 v[34:35], v[34:35], v[2:3] op_sel_hi:[1,0]
	v_pk_mul_f32 v[32:33], v[32:33], v[2:3] op_sel_hi:[1,0]
	v_pk_mul_f32 v[62:63], v[62:63], v[2:3] op_sel_hi:[1,0]
	v_pk_mul_f32 v[60:61], v[60:61], v[2:3] op_sel_hi:[1,0]
	v_pk_mul_f32 v[58:59], v[58:59], v[2:3] op_sel_hi:[1,0]
	v_pk_mul_f32 v[56:57], v[56:57], v[2:3] op_sel_hi:[1,0]
	v_pk_mul_f32 v[54:55], v[54:55], v[2:3] op_sel_hi:[1,0]
	v_pk_mul_f32 v[52:53], v[52:53], v[2:3] op_sel_hi:[1,0]
	v_pk_mul_f32 v[50:51], v[50:51], v[2:3] op_sel_hi:[1,0]
	v_pk_mul_f32 v[48:49], v[48:49], v[2:3] op_sel_hi:[1,0]
	v_mul_f32_e32 v161, v161, v2
	v_sub_f32_e32 v163, v163, v3
	v_sub_f32_e32 v82, v82, v3
	v_sub_f32_e32 v15, v15, v3
	v_sub_f32_e32 v84, v84, v3
	v_sub_f32_e32 v83, v83, v3
	v_sub_f32_e32 v86, v86, v3
	v_sub_f32_e32 v85, v85, v3
	v_sub_f32_e32 v88, v88, v3
	v_sub_f32_e32 v87, v87, v3
	v_sub_f32_e32 v90, v90, v3
	v_sub_f32_e32 v89, v89, v3
	v_sub_f32_e32 v92, v92, v3
	v_sub_f32_e32 v91, v91, v3
	v_sub_f32_e32 v80, v80, v3
	v_sub_f32_e32 v14, v14, v3
	v_sub_f32_e32 v79, v79, v3
	v_sub_f32_e32 v78, v78, v3
	v_sub_f32_e32 v77, v77, v3
	v_sub_f32_e32 v76, v76, v3
	v_sub_f32_e32 v75, v75, v3
	v_sub_f32_e32 v74, v74, v3
	v_sub_f32_e32 v73, v73, v3
	v_sub_f32_e32 v72, v72, v3
	v_sub_f32_e32 v71, v71, v3
	v_sub_f32_e32 v70, v70, v3
	v_sub_f32_e32 v69, v69, v3
	v_sub_f32_e32 v68, v68, v3
	v_sub_f32_e32 v67, v67, v3
	v_sub_f32_e32 v66, v66, v3
	v_sub_f32_e32 v65, v65, v3
	v_sub_f32_e32 v64, v64, v3
	v_mov_b32_e32 v17, v16
	v_mov_b32_e32 v18, v16
	v_mov_b32_e32 v19, v16
	v_mov_b32_e32 v20, v16
	v_mov_b32_e32 v21, v16
	v_mov_b32_e32 v22, v16
	v_mov_b32_e32 v23, v16
	v_mov_b32_e32 v24, v16
	v_mov_b32_e32 v25, v16
	v_mov_b32_e32 v26, v16
	v_mov_b32_e32 v27, v16
	v_mov_b32_e32 v28, v16
	v_mov_b32_e32 v29, v16
	v_mov_b32_e32 v30, v16
	v_mov_b32_e32 v31, v16
